# v29 + stagger barrier of the second wave half moved behind its K-tile 1 DMA pieces
# speedup vs baseline: 1.0063x; 1.0063x over previous
.Lstg_6:
	s_waitcnt vmcnt(8)
	s_barrier
	v_bfe_u32 v59, v37, 4, 2
	v_and_b32_e32 v58, 15, v37
	v_lshlrev_b32_e32 v185, 4, v59
	v_lshlrev_b32_e32 v37, 2, v37
	v_lshl_or_b32 v184, s11, 6, v58
	v_lshl_or_b32 v58, v58, 6, v185
	s_lshl_b32 s11, s11, 13
	v_and_b32_e32 v37, 32, v37
	v_bitop3_b32 v84, v58, s11, v37 bitop3:0xde
	s_lshl_b32 s11, s1, 12
	v_bitop3_b32 v186, v58, s11, v37 bitop3:0xde
	s_cmpk_lt_u32 s0, 0x100
	v_lshrrev_b32_e32 v37, 1, v56
	v_mul_lo_u32 v58, v39, s7
	s_mov_b32 s11, 0x2c000
	s_cselect_b64 s[60:61], -1, 0
	v_cmp_eq_u32_e64 s[38:39], 0, v59
	s_lshl_b32 s26, s1, 1
	v_lshl_or_b32 v187, s1, 6, v185
	v_mad_u64_u32 v[58:59], s[0:1], v37, s11, v[58:59]
	v_and_b32_e32 v37, 1, v56
	v_lshl_or_b32 v37, v37, 6, v58
	v_lshl_add_u32 v176, v57, 1, v37
	v_lshrrev_b32_e32 v37, 1, v36
	v_mad_u64_u32 v[56:57], s[0:1], v37, s11, v[26:27]
	s_waitcnt vmcnt(6)
	v_and_b32_e32 v26, 1, v36
	v_readlane_b32 s0, v251, 36
	v_lshl_or_b32 v26, v26, 6, v56
	s_mov_b32 s94, s0
	v_readlane_b32 s0, v251, 34
	v_readlane_b32 s78, v251, 37
	s_mov_b32 s81, 0
	s_orn2_b32 s26, s26, 47
	v_mov_b32_e32 v177, v27
	v_lshl_add_u32 v178, v38, 1, v26
	v_mov_b32_e32 v179, v27
	v_add_u32_e32 v188, 0, v84
	v_readlane_b32 s31, v251, 35
	s_mov_b32 s30, s0
	s_mov_b64 s[76:77], s[86:87]
	v_readlane_b32 s79, v251, 38
	s_barrier
	s_mov_b32 s98, 0
	s_branch .LBB0_108
